# GEMM main loops (in-proj, out-proj, FFN1, FFN2): hipcc's per-segment s_setprio flips deleted
# speedup vs baseline: 1.0080x; 1.0073x over previous
; #define PG8_STAGE(bufoff, gbase, voff) do { _Pragma("unroll") for (int _i = 0; _i < 2; ++_i) \
;         __builtin_amdgcn_global_load_lds((const unsigned*)((const char*)(gbase) + (voff)[_i]), (LAS unsigned*)(lds + (bufoff) + ldsw + _i * 8192), 16, 0, 0); } while (0)
; #define PG8_LDA(dst, b, h) do { _Pragma("unroll") for (int m = 0; m < 4; ++m) _Pragma("unroll") for (int k = 0; k < 2; ++k) dst[m][k] = *(const LAS bf16x8*)(lds + PG8_SA(b, h) + aoff + m * 2048 + k * 1024); } while (0)
; #define PG8_LDB(dst, b, h) do { _Pragma("unroll") for (int n = 0; n < 2; ++n) _Pragma("unroll") for (int k = 0; k < 2; ++k) dst[n][k] = *(const LAS bf16x8*)(lds + PG8_SB(b, h) + boff + n * 2048 + k * 1024); } while (0)
; #define PG8_MMA(ai, bj, At, Bt) do { __builtin_amdgcn_s_setprio(1); _Pragma("unroll") for (int m = 0; m < 4; ++m) _Pragma("unroll") for (int n = 0; n < 2; ++n) _Pragma("unroll") for (int k = 0; k < 2; ++k) \
;         acc[ai][bj][m][n] = __builtin_amdgcn_mfma_f32_16x16x32_bf16(Bt[n][k], At[m][k], acc[ai][bj][m][n], 0, 0, 0); __builtin_amdgcn_s_setprio(0); } while (0)
; #define PG8_WAIT_L(n) asm volatile("s_waitcnt lgkmcnt(" #n ")" ::: "memory")
; #define PG8_BAR __builtin_amdgcn_s_barrier()
; #define PG8_SCHED __builtin_amdgcn_sched_barrier(0)
; template <class Epi>
; __device__ __forceinline__ void gemm_phase(LAS unsigned char* lds, const Gemm g, const StaticOrder& S, const Epi& E) {
;     ...
;             PG8_LDB(B0, 0, 0); PG8_SCHED; PG8_LDA(At, 0, 0); PG8_STAGE(PG8_SA(1, 1), a1 + hstep, voffA);
;             PG8_WAIT_L(8); PG8_BAR; PG8_WAIT_L(0); PG8_MMA(0, 0, At, B0); PG8_BAR; PG8_SCHED;
;             PG8_LDB(B1, 0, 1); PG8_STAGE(PG8_SB(0, 0), b2, voffB);
;             PG8_BAR; PG8_WAIT_L(0); PG8_MMA(0, 1, At, B1); PG8_BAR;
;             PG8_LDA(At, 0, 1); PG8_STAGE(PG8_SA(0, 0), a2, voffA);
;             PG8_BAR; PG8_WAIT_L(0); PG8_MMA(1, 0, At, B0); PG8_BAR; PG8_SCHED;
.LBB0_119:
	s_add_i32 s41, s16, 2
	s_add_u32 s18, s14, 0x80
	s_addc_u32 s17, s15, 0
	s_add_i32 s42, 0, 0x10000
	v_add_u32_e32 v140, s42, v245
	ds_read_b128 v[128:131], v140
	ds_read_b128 v[132:135], v140 offset:1024
	ds_read_b128 v[136:139], v140 offset:2048
	ds_read_b128 v[140:143], v140 offset:3072
	s_cmp_eq_u32 s31, s16
	s_cselect_b32 s16, s10, s18
	s_cselect_b32 s17, s11, s17
	s_cselect_b32 s19, s13, s40
	s_cselect_b32 s18, s12, s39
	v_lshl_add_u64 v[176:177], s[14:15], 0, v[210:211]
	s_add_i32 m0, s24, 0xc000
	ds_read_b128 v[144:147], v247
	ds_read_b128 v[148:151], v247 offset:1024
	ds_read_b128 v[152:155], v247 offset:2048
	ds_read_b128 v[156:159], v247 offset:3072
	ds_read_b128 v[160:163], v247 offset:4096
	ds_read_b128 v[164:167], v247 offset:5120
	ds_read_b128 v[168:171], v247 offset:6144
	ds_read_b128 v[172:175], v247 offset:7168
	global_load_lds_dwordx4 v[176:177], off
	v_lshl_add_u64 v[176:177], s[14:15], 0, v[208:209]
	s_add_i32 m0, s24, 0xe000
	s_nop 0
	global_load_lds_dwordx4 v[176:177], off
	s_waitcnt lgkmcnt(8)
	s_barrier
	s_waitcnt lgkmcnt(0)
	s_waitcnt lgkmcnt(0)
	v_mfma_f32_16x16x32_bf16 v[124:127], v[128:131], v[144:147], v[124:127]
	v_mfma_f32_16x16x32_bf16 v[120:123], v[136:139], v[144:147], v[120:123]
	v_mfma_f32_16x16x32_bf16 v[108:111], v[128:131], v[152:155], v[108:111]
	v_mfma_f32_16x16x32_bf16 v[104:107], v[136:139], v[152:155], v[104:107]
	v_mfma_f32_16x16x32_bf16 v[92:95], v[128:131], v[160:163], v[92:95]
	v_mfma_f32_16x16x32_bf16 v[88:91], v[136:139], v[160:163], v[88:91]
	v_mfma_f32_16x16x32_bf16 v[76:79], v[128:131], v[168:171], v[76:79]
	v_mfma_f32_16x16x32_bf16 v[72:75], v[136:139], v[168:171], v[72:75]
	v_mfma_f32_16x16x32_bf16 v[124:127], v[132:135], v[148:151], v[124:127]
	v_mfma_f32_16x16x32_bf16 v[120:123], v[140:143], v[148:151], v[120:123]
	v_mfma_f32_16x16x32_bf16 v[108:111], v[132:135], v[156:159], v[108:111]
	v_mfma_f32_16x16x32_bf16 v[104:107], v[140:143], v[156:159], v[104:107]
	v_mfma_f32_16x16x32_bf16 v[92:95], v[132:135], v[164:167], v[92:95]
	v_mfma_f32_16x16x32_bf16 v[88:91], v[140:143], v[164:167], v[88:91]
	v_mfma_f32_16x16x32_bf16 v[76:79], v[132:135], v[172:175], v[76:79]
	v_mfma_f32_16x16x32_bf16 v[72:75], v[140:143], v[172:175], v[72:75]
	s_barrier
	s_add_i32 s43, 0, 0x14000
	s_add_i32 s42, s42, s23
	v_add_u32_e32 v188, s43, v245
	v_lshl_add_u64 v[212:213], s[18:19], 0, v[194:195]
	s_mov_b32 m0, s42
	ds_read_b128 v[176:179], v188
	ds_read_b128 v[180:183], v188 offset:1024
	ds_read_b128 v[184:187], v188 offset:2048
	ds_read_b128 v[188:191], v188 offset:3072
	global_load_lds_dwordx4 v[212:213], off
	v_lshl_add_u64 v[214:215], s[18:19], 0, v[206:207]
	s_add_i32 m0, s42, 0x2000
	s_nop 0
	global_load_lds_dwordx4 v[214:215], off
	s_barrier
	s_waitcnt lgkmcnt(0)
	s_waitcnt lgkmcnt(0)
	v_mfma_f32_16x16x32_bf16 v[116:119], v[176:179], v[144:147], v[116:119]
	v_mfma_f32_16x16x32_bf16 v[112:115], v[184:187], v[144:147], v[112:115]
	v_mfma_f32_16x16x32_bf16 v[100:103], v[176:179], v[152:155], v[100:103]
	v_mfma_f32_16x16x32_bf16 v[96:99], v[184:187], v[152:155], v[96:99]
	v_mfma_f32_16x16x32_bf16 v[84:87], v[176:179], v[160:163], v[84:87]
	v_mfma_f32_16x16x32_bf16 v[80:83], v[184:187], v[160:163], v[80:83]
	v_mfma_f32_16x16x32_bf16 v[68:71], v[176:179], v[168:171], v[68:71]
	v_mfma_f32_16x16x32_bf16 v[64:67], v[184:187], v[168:171], v[64:67]
	v_mfma_f32_16x16x32_bf16 v[116:119], v[180:183], v[148:151], v[116:119]
	v_mfma_f32_16x16x32_bf16 v[112:115], v[188:191], v[148:151], v[112:115]
	v_mfma_f32_16x16x32_bf16 v[100:103], v[180:183], v[156:159], v[100:103]
	v_mfma_f32_16x16x32_bf16 v[96:99], v[188:191], v[156:159], v[96:99]
	v_mfma_f32_16x16x32_bf16 v[84:87], v[180:183], v[164:167], v[84:87]
	v_mfma_f32_16x16x32_bf16 v[80:83], v[188:191], v[164:167], v[80:83]
	v_mfma_f32_16x16x32_bf16 v[68:71], v[180:183], v[172:175], v[68:71]
	v_mfma_f32_16x16x32_bf16 v[64:67], v[188:191], v[172:175], v[64:67]
	s_mov_b32 m0, s24
	v_lshl_add_u64 v[216:217], s[16:17], 0, v[202:203]
	s_barrier
	ds_read_b128 v[144:147], v247 offset:16384
	ds_read_b128 v[148:151], v247 offset:17408
	ds_read_b128 v[152:155], v247 offset:18432
	ds_read_b128 v[156:159], v247 offset:19456
	ds_read_b128 v[160:163], v247 offset:20480
	ds_read_b128 v[164:167], v247 offset:21504
	ds_read_b128 v[168:171], v247 offset:22528
	ds_read_b128 v[172:175], v247 offset:23552
	global_load_lds_dwordx4 v[216:217], off
	v_lshl_add_u64 v[218:219], s[16:17], 0, v[204:205]
	s_mov_b32 m0, s25
	s_nop 0
	global_load_lds_dwordx4 v[218:219], off
	s_barrier
	s_waitcnt lgkmcnt(0)
	s_waitcnt lgkmcnt(0)
	v_mfma_f32_16x16x32_bf16 v[60:63], v[128:131], v[144:147], v[60:63]
	v_mfma_f32_16x16x32_bf16 v[56:59], v[136:139], v[144:147], v[56:59]
	v_mfma_f32_16x16x32_bf16 v[44:47], v[128:131], v[152:155], v[44:47]
	v_mfma_f32_16x16x32_bf16 v[40:43], v[136:139], v[152:155], v[40:43]
	v_mfma_f32_16x16x32_bf16 v[28:31], v[128:131], v[160:163], v[28:31]
	v_mfma_f32_16x16x32_bf16 v[24:27], v[136:139], v[160:163], v[24:27]
	v_mfma_f32_16x16x32_bf16 v[12:15], v[128:131], v[168:171], v[12:15]
	v_mfma_f32_16x16x32_bf16 v[8:11], v[136:139], v[168:171], v[8:11]
	v_mfma_f32_16x16x32_bf16 v[60:63], v[132:135], v[148:151], v[60:63]
	v_mfma_f32_16x16x32_bf16 v[56:59], v[140:143], v[148:151], v[56:59]
	v_mfma_f32_16x16x32_bf16 v[44:47], v[132:135], v[156:159], v[44:47]
	v_mfma_f32_16x16x32_bf16 v[40:43], v[140:143], v[156:159], v[40:43]
	v_mfma_f32_16x16x32_bf16 v[28:31], v[132:135], v[164:167], v[28:31]
	v_mfma_f32_16x16x32_bf16 v[24:27], v[140:143], v[164:167], v[24:27]
	v_mfma_f32_16x16x32_bf16 v[12:15], v[132:135], v[172:175], v[12:15]
	v_mfma_f32_16x16x32_bf16 v[8:11], v[140:143], v[172:175], v[8:11]
	s_barrier
; #define PG8_STAGE(bufoff, gbase, voff) do { _Pragma("unroll") for (int _i = 0; _i < 2; ++_i) \
;         __builtin_amdgcn_global_load_lds((const unsigned*)((const char*)(gbase) + (voff)[_i]), (LAS unsigned*)(lds + (bufoff) + ldsw + _i * 8192), 16, 0, 0); } while (0)
; #define PG8_LDA(dst, b, h) do { _Pragma("unroll") for (int m = 0; m < 4; ++m) _Pragma("unroll") for (int k = 0; k < 2; ++k) dst[m][k] = *(const LAS bf16x8*)(lds + PG8_SA(b, h) + aoff + m * 2048 + k * 1024); } while (0)
; #define PG8_LDB(dst, b, h) do { _Pragma("unroll") for (int n = 0; n < 2; ++n) _Pragma("unroll") for (int k = 0; k < 2; ++k) dst[n][k] = *(const LAS bf16x8*)(lds + PG8_SB(b, h) + boff + n * 2048 + k * 1024); } while (0)
; #define PG8_MMA(ai, bj, At, Bt) do { __builtin_amdgcn_s_setprio(1); _Pragma("unroll") for (int m = 0; m < 4; ++m) _Pragma("unroll") for (int n = 0; n < 2; ++n) _Pragma("unroll") for (int k = 0; k < 2; ++k) \
;         acc[ai][bj][m][n] = __builtin_amdgcn_mfma_f32_16x16x32_bf16(Bt[n][k], At[m][k], acc[ai][bj][m][n], 0, 0, 0); __builtin_amdgcn_s_setprio(0); } while (0)
; #define PG8_WAIT_V(n) asm volatile("s_waitcnt vmcnt(" #n ")" ::: "memory")
; #define PG8_WAIT_L(n) asm volatile("s_waitcnt lgkmcnt(" #n ")" ::: "memory")
; #define PG8_BAR __builtin_amdgcn_s_barrier()
; #define PG8_SCHED __builtin_amdgcn_sched_barrier(0)
; template <class Epi>
; __device__ __forceinline__ void gemm_phase(LAS unsigned char* lds, const Gemm g, const StaticOrder& S, const Epi& E) {
;     ...
;             PG8_STAGE(PG8_SB(0, 1), b2 + hstep, voffB);
;             PG8_WAIT_V(6); PG8_BAR; PG8_MMA(1, 1, At, B1); PG8_BAR;
;             PG8_LDB(B0, 1, 0); PG8_SCHED; PG8_LDA(At, 1, 0); PG8_STAGE(PG8_SA(0, 1), a2 + hstep, voffA);
;             PG8_WAIT_L(8); PG8_BAR; PG8_WAIT_L(0); PG8_MMA(0, 0, At, B0); PG8_BAR; PG8_SCHED;
;             PG8_LDB(B1, 1, 1); PG8_STAGE(PG8_SB(1, 0), b3, voffB);
;             PG8_BAR; PG8_WAIT_L(0); PG8_MMA(0, 1, At, B1); PG8_BAR;
	s_add_u32 s18, s18, s0
	s_addc_u32 s19, s19, s1
	s_add_i32 s42, s43, s23
	v_lshl_add_u64 v[220:221], s[18:19], 0, v[194:195]
	s_mov_b32 m0, s42
	v_lshl_add_u64 v[222:223], s[18:19], 0, v[206:207]
	global_load_lds_dwordx4 v[220:221], off
	s_add_i32 m0, s42, 0x2000
	s_nop 0
	global_load_lds_dwordx4 v[222:223], off
	s_waitcnt vmcnt(6)
	s_barrier
	v_mfma_f32_16x16x32_bf16 v[52:55], v[176:179], v[144:147], v[52:55]
	v_mfma_f32_16x16x32_bf16 v[48:51], v[184:187], v[144:147], v[48:51]
	v_mfma_f32_16x16x32_bf16 v[36:39], v[176:179], v[152:155], v[36:39]
	v_mfma_f32_16x16x32_bf16 v[32:35], v[184:187], v[152:155], v[32:35]
	v_mfma_f32_16x16x32_bf16 v[20:23], v[176:179], v[160:163], v[20:23]
	v_mfma_f32_16x16x32_bf16 v[16:19], v[184:187], v[160:163], v[16:19]
	v_mfma_f32_16x16x32_bf16 v[4:7], v[176:179], v[168:171], v[4:7]
	v_mfma_f32_16x16x32_bf16 v[0:3], v[184:187], v[168:171], v[0:3]
	v_mfma_f32_16x16x32_bf16 v[52:55], v[180:183], v[148:151], v[52:55]
	v_mfma_f32_16x16x32_bf16 v[48:51], v[188:191], v[148:151], v[48:51]
	v_mfma_f32_16x16x32_bf16 v[36:39], v[180:183], v[156:159], v[36:39]
	v_mfma_f32_16x16x32_bf16 v[32:35], v[188:191], v[156:159], v[32:35]
	v_mfma_f32_16x16x32_bf16 v[20:23], v[180:183], v[164:167], v[20:23]
	v_mfma_f32_16x16x32_bf16 v[16:19], v[188:191], v[164:167], v[16:19]
	v_mfma_f32_16x16x32_bf16 v[4:7], v[180:183], v[172:175], v[4:7]
	v_mfma_f32_16x16x32_bf16 v[0:3], v[188:191], v[172:175], v[0:3]
	s_add_i32 s18, 0, 0x18000
	v_add_u32_e32 v140, s18, v245
	s_barrier
	ds_read_b128 v[128:131], v140
	ds_read_b128 v[132:135], v140 offset:1024
	ds_read_b128 v[136:139], v140 offset:2048
	ds_read_b128 v[140:143], v140 offset:3072
	s_add_u32 s16, s16, s0
	s_addc_u32 s17, s17, s1
	s_mov_b32 m0, s26
	v_lshl_add_u64 v[176:177], s[16:17], 0, v[202:203]
	ds_read_b128 v[144:147], v247 offset:32768
	ds_read_b128 v[148:151], v247 offset:33792
	ds_read_b128 v[152:155], v247 offset:34816
	ds_read_b128 v[156:159], v247 offset:35840
	ds_read_b128 v[160:163], v247 offset:36864
	ds_read_b128 v[164:167], v247 offset:37888
	ds_read_b128 v[168:171], v247 offset:38912
	ds_read_b128 v[172:175], v247 offset:39936
	global_load_lds_dwordx4 v[176:177], off
	v_lshl_add_u64 v[176:177], s[16:17], 0, v[204:205]
	s_mov_b32 m0, s27
	s_nop 0
	global_load_lds_dwordx4 v[176:177], off
	s_waitcnt lgkmcnt(8)
	s_barrier
	s_waitcnt lgkmcnt(0)
	s_waitcnt lgkmcnt(0)
	v_mfma_f32_16x16x32_bf16 v[124:127], v[128:131], v[144:147], v[124:127]
	v_mfma_f32_16x16x32_bf16 v[120:123], v[136:139], v[144:147], v[120:123]
	v_mfma_f32_16x16x32_bf16 v[108:111], v[128:131], v[152:155], v[108:111]
	v_mfma_f32_16x16x32_bf16 v[104:107], v[136:139], v[152:155], v[104:107]
	v_mfma_f32_16x16x32_bf16 v[92:95], v[128:131], v[160:163], v[92:95]
	v_mfma_f32_16x16x32_bf16 v[88:91], v[136:139], v[160:163], v[88:91]
	v_mfma_f32_16x16x32_bf16 v[76:79], v[128:131], v[168:171], v[76:79]
	v_mfma_f32_16x16x32_bf16 v[72:75], v[136:139], v[168:171], v[72:75]
	v_mfma_f32_16x16x32_bf16 v[124:127], v[132:135], v[148:151], v[124:127]
	v_mfma_f32_16x16x32_bf16 v[120:123], v[140:143], v[148:151], v[120:123]
	v_mfma_f32_16x16x32_bf16 v[108:111], v[132:135], v[156:159], v[108:111]
	v_mfma_f32_16x16x32_bf16 v[104:107], v[140:143], v[156:159], v[104:107]
	v_mfma_f32_16x16x32_bf16 v[92:95], v[132:135], v[164:167], v[92:95]
	v_mfma_f32_16x16x32_bf16 v[88:91], v[140:143], v[164:167], v[88:91]
	v_mfma_f32_16x16x32_bf16 v[76:79], v[132:135], v[172:175], v[76:79]
	v_mfma_f32_16x16x32_bf16 v[72:75], v[140:143], v[172:175], v[72:75]
	s_barrier
	s_add_i32 s16, 0, 0x1c000
	s_add_i32 s17, s18, s23
	v_add_u32_e32 v188, s16, v245
	v_lshl_add_u64 v[212:213], v[212:213], 0, s[44:45]
	s_mov_b32 m0, s17
	ds_read_b128 v[176:179], v188
	ds_read_b128 v[180:183], v188 offset:1024
	ds_read_b128 v[184:187], v188 offset:2048
	ds_read_b128 v[188:191], v188 offset:3072
	global_load_lds_dwordx4 v[212:213], off
	v_lshl_add_u64 v[212:213], v[214:215], 0, s[44:45]
	s_add_i32 m0, s17, 0x2000
	s_nop 0
	global_load_lds_dwordx4 v[212:213], off
	s_barrier
; #define PG8_STAGE(bufoff, gbase, voff) do { _Pragma("unroll") for (int _i = 0; _i < 2; ++_i) \
;         __builtin_amdgcn_global_load_lds((const unsigned*)((const char*)(gbase) + (voff)[_i]), (LAS unsigned*)(lds + (bufoff) + ldsw + _i * 8192), 16, 0, 0); } while (0)
; #define PG8_LDA(dst, b, h) do { _Pragma("unroll") for (int m = 0; m < 4; ++m) _Pragma("unroll") for (int k = 0; k < 2; ++k) dst[m][k] = *(const LAS bf16x8*)(lds + PG8_SA(b, h) + aoff + m * 2048 + k * 1024); } while (0)
; #define PG8_MMA(ai, bj, At, Bt) do { __builtin_amdgcn_s_setprio(1); _Pragma("unroll") for (int m = 0; m < 4; ++m) _Pragma("unroll") for (int n = 0; n < 2; ++n) _Pragma("unroll") for (int k = 0; k < 2; ++k) \
;         acc[ai][bj][m][n] = __builtin_amdgcn_mfma_f32_16x16x32_bf16(Bt[n][k], At[m][k], acc[ai][bj][m][n], 0, 0, 0); __builtin_amdgcn_s_setprio(0); } while (0)
; #define PG8_WAIT_V(n) asm volatile("s_waitcnt vmcnt(" #n ")" ::: "memory")
; #define PG8_WAIT_L(n) asm volatile("s_waitcnt lgkmcnt(" #n ")" ::: "memory")
; #define PG8_BAR __builtin_amdgcn_s_barrier()
; #define PG8_SCHED __builtin_amdgcn_sched_barrier(0)
; template <class Epi>
; __device__ __forceinline__ void gemm_phase(LAS unsigned char* lds, const Gemm g, const StaticOrder& S, const Epi& E) {
;     ...
;             PG8_BAR; PG8_WAIT_L(0); PG8_MMA(0, 1, At, B1); PG8_BAR;
;             PG8_LDA(At, 1, 1); PG8_STAGE(PG8_SA(1, 0), a3, voffA);
;             PG8_BAR; PG8_WAIT_L(0); PG8_MMA(1, 0, At, B0); PG8_BAR; PG8_SCHED;
;             PG8_STAGE(PG8_SB(1, 1), b3 + hstep, voffB);
;             PG8_WAIT_V(6); PG8_BAR; PG8_MMA(1, 1, At, B1); PG8_BAR;
;         }
	s_waitcnt lgkmcnt(0)
	s_waitcnt lgkmcnt(0)
	v_mfma_f32_16x16x32_bf16 v[116:119], v[176:179], v[144:147], v[116:119]
	v_mfma_f32_16x16x32_bf16 v[112:115], v[184:187], v[144:147], v[112:115]
	v_mfma_f32_16x16x32_bf16 v[100:103], v[176:179], v[152:155], v[100:103]
	v_mfma_f32_16x16x32_bf16 v[96:99], v[184:187], v[152:155], v[96:99]
	v_mfma_f32_16x16x32_bf16 v[84:87], v[176:179], v[160:163], v[84:87]
	v_mfma_f32_16x16x32_bf16 v[80:83], v[184:187], v[160:163], v[80:83]
	v_mfma_f32_16x16x32_bf16 v[68:71], v[176:179], v[168:171], v[68:71]
	v_mfma_f32_16x16x32_bf16 v[64:67], v[184:187], v[168:171], v[64:67]
	v_mfma_f32_16x16x32_bf16 v[116:119], v[180:183], v[148:151], v[116:119]
	v_mfma_f32_16x16x32_bf16 v[112:115], v[188:191], v[148:151], v[112:115]
	v_mfma_f32_16x16x32_bf16 v[100:103], v[180:183], v[156:159], v[100:103]
	v_mfma_f32_16x16x32_bf16 v[96:99], v[188:191], v[156:159], v[96:99]
	v_mfma_f32_16x16x32_bf16 v[84:87], v[180:183], v[164:167], v[84:87]
	v_mfma_f32_16x16x32_bf16 v[80:83], v[188:191], v[164:167], v[80:83]
	v_mfma_f32_16x16x32_bf16 v[68:71], v[180:183], v[172:175], v[68:71]
	v_mfma_f32_16x16x32_bf16 v[64:67], v[188:191], v[172:175], v[64:67]
	s_mov_b32 m0, s28
	v_lshl_add_u64 v[212:213], v[216:217], 0, s[44:45]
	s_barrier
	ds_read_b128 v[144:147], v247 offset:49152
	ds_read_b128 v[148:151], v247 offset:50176
	ds_read_b128 v[152:155], v247 offset:51200
	ds_read_b128 v[156:159], v247 offset:52224
	ds_read_b128 v[160:163], v247 offset:53248
	ds_read_b128 v[164:167], v247 offset:54272
	ds_read_b128 v[168:171], v247 offset:55296
	ds_read_b128 v[172:175], v247 offset:56320
	global_load_lds_dwordx4 v[212:213], off
	v_lshl_add_u64 v[212:213], v[218:219], 0, s[44:45]
	s_mov_b32 m0, s29
	s_nop 0
	global_load_lds_dwordx4 v[212:213], off
	s_barrier
	s_waitcnt lgkmcnt(0)
	s_waitcnt lgkmcnt(0)
	v_mfma_f32_16x16x32_bf16 v[60:63], v[128:131], v[144:147], v[60:63]
	v_mfma_f32_16x16x32_bf16 v[56:59], v[136:139], v[144:147], v[56:59]
	v_mfma_f32_16x16x32_bf16 v[44:47], v[128:131], v[152:155], v[44:47]
	v_mfma_f32_16x16x32_bf16 v[40:43], v[136:139], v[152:155], v[40:43]
	v_mfma_f32_16x16x32_bf16 v[28:31], v[128:131], v[160:163], v[28:31]
	v_mfma_f32_16x16x32_bf16 v[24:27], v[136:139], v[160:163], v[24:27]
	v_mfma_f32_16x16x32_bf16 v[12:15], v[128:131], v[168:171], v[12:15]
	v_mfma_f32_16x16x32_bf16 v[8:11], v[136:139], v[168:171], v[8:11]
	v_mfma_f32_16x16x32_bf16 v[60:63], v[132:135], v[148:151], v[60:63]
	v_mfma_f32_16x16x32_bf16 v[56:59], v[140:143], v[148:151], v[56:59]
	v_mfma_f32_16x16x32_bf16 v[44:47], v[132:135], v[156:159], v[44:47]
	v_mfma_f32_16x16x32_bf16 v[40:43], v[140:143], v[156:159], v[40:43]
	v_mfma_f32_16x16x32_bf16 v[28:31], v[132:135], v[164:167], v[28:31]
	v_mfma_f32_16x16x32_bf16 v[24:27], v[140:143], v[164:167], v[24:27]
	v_mfma_f32_16x16x32_bf16 v[12:15], v[132:135], v[172:175], v[12:15]
	v_mfma_f32_16x16x32_bf16 v[8:11], v[140:143], v[172:175], v[8:11]
	s_barrier
	s_add_i32 s16, s16, s23
	v_lshl_add_u64 v[128:129], v[220:221], 0, s[44:45]
	s_mov_b32 m0, s16
	s_nop 0
	global_load_lds_dwordx4 v[128:129], off
	v_lshl_add_u64 v[128:129], v[222:223], 0, s[44:45]
	s_add_i32 m0, s16, 0x2000
	s_nop 0
	global_load_lds_dwordx4 v[128:129], off
	s_waitcnt vmcnt(6)
	s_barrier
	v_mfma_f32_16x16x32_bf16 v[52:55], v[176:179], v[144:147], v[52:55]
	v_mfma_f32_16x16x32_bf16 v[48:51], v[184:187], v[144:147], v[48:51]
	v_mfma_f32_16x16x32_bf16 v[36:39], v[176:179], v[152:155], v[36:39]
	v_mfma_f32_16x16x32_bf16 v[32:35], v[184:187], v[152:155], v[32:35]
	v_mfma_f32_16x16x32_bf16 v[20:23], v[176:179], v[160:163], v[20:23]
	v_mfma_f32_16x16x32_bf16 v[16:19], v[184:187], v[160:163], v[16:19]
	v_mfma_f32_16x16x32_bf16 v[4:7], v[176:179], v[168:171], v[4:7]
	v_mfma_f32_16x16x32_bf16 v[0:3], v[184:187], v[168:171], v[0:3]
	v_mfma_f32_16x16x32_bf16 v[52:55], v[180:183], v[148:151], v[52:55]
	v_mfma_f32_16x16x32_bf16 v[48:51], v[188:191], v[148:151], v[48:51]
	v_mfma_f32_16x16x32_bf16 v[36:39], v[180:183], v[156:159], v[36:39]
	v_mfma_f32_16x16x32_bf16 v[32:35], v[188:191], v[156:159], v[32:35]
	v_mfma_f32_16x16x32_bf16 v[20:23], v[180:183], v[164:167], v[20:23]
	v_mfma_f32_16x16x32_bf16 v[16:19], v[188:191], v[164:167], v[16:19]
	v_mfma_f32_16x16x32_bf16 v[4:7], v[180:183], v[172:175], v[4:7]
	v_mfma_f32_16x16x32_bf16 v[0:3], v[188:191], v[172:175], v[0:3]
	s_add_u32 s39, s39, 0x100
	s_addc_u32 s40, s40, 0
	s_add_u32 s14, s14, 0x100
	s_addc_u32 s15, s15, 0
	s_cmp_ge_i32 s41, s30
	s_mov_b32 s16, s41
	s_barrier
	s_cbranch_scc0 .LBB0_119

; #define PG8_STAGE(bufoff, gbase, voff) do { _Pragma("unroll") for (int _i = 0; _i < 2; ++_i) \
;         __builtin_amdgcn_global_load_lds((const unsigned*)((const char*)(gbase) + (voff)[_i]), (LAS unsigned*)(lds + (bufoff) + ldsw + _i * 8192), 16, 0, 0); } while (0)
; #define PG8_LDA(dst, b, h) do { _Pragma("unroll") for (int m = 0; m < 4; ++m) _Pragma("unroll") for (int k = 0; k < 2; ++k) dst[m][k] = *(const LAS bf16x8*)(lds + PG8_SA(b, h) + aoff + m * 2048 + k * 1024); } while (0)
; #define PG8_LDB(dst, b, h) do { _Pragma("unroll") for (int n = 0; n < 2; ++n) _Pragma("unroll") for (int k = 0; k < 2; ++k) dst[n][k] = *(const LAS bf16x8*)(lds + PG8_SB(b, h) + boff + n * 2048 + k * 1024); } while (0)
; #define PG8_MMA(ai, bj, At, Bt) do { __builtin_amdgcn_s_setprio(1); _Pragma("unroll") for (int m = 0; m < 4; ++m) _Pragma("unroll") for (int n = 0; n < 2; ++n) _Pragma("unroll") for (int k = 0; k < 2; ++k) \
;         acc[ai][bj][m][n] = __builtin_amdgcn_mfma_f32_16x16x32_bf16(Bt[n][k], At[m][k], acc[ai][bj][m][n], 0, 0, 0); __builtin_amdgcn_s_setprio(0); } while (0)
; #define PG8_WAIT_L(n) asm volatile("s_waitcnt lgkmcnt(" #n ")" ::: "memory")
; #define PG8_BAR __builtin_amdgcn_s_barrier()
; #define PG8_SCHED __builtin_amdgcn_sched_barrier(0)
; template <class Epi>
; __device__ __forceinline__ void gemm_phase(LAS unsigned char* lds, const Gemm g, const StaticOrder& S, const Epi& E) {
;     ...
;         for (int t = 0; t < nt; t += 2) {
;             const bool last = (t == nt - 2);
;             const char* a1 = cA + (size_t)(t + 1) * kstep;
;             const char* a2 = last ? nA : cA + (size_t)(t + 2) * kstep; const char* b2 = last ? nB : cB + (size_t)(t + 2) * kstep;
;             const char* a3 = a2 + kstep; const char* b3 = b2 + kstep;
;             PG8_LDB(B0, 0, 0); PG8_SCHED; PG8_LDA(At, 0, 0); PG8_STAGE(PG8_SA(1, 1), a1 + hstep, voffA);
;             PG8_WAIT_L(8); PG8_BAR; PG8_WAIT_L(0); PG8_MMA(0, 0, At, B0); PG8_BAR; PG8_SCHED;
;             PG8_LDB(B1, 0, 1); PG8_STAGE(PG8_SB(0, 0), b2, voffB);
;             PG8_BAR; PG8_WAIT_L(0); PG8_MMA(0, 1, At, B1); PG8_BAR;
;             PG8_LDA(At, 0, 1); PG8_STAGE(PG8_SA(0, 0), a2, voffA);
;             PG8_BAR; PG8_WAIT_L(0); PG8_MMA(1, 0, At, B0); PG8_BAR; PG8_SCHED;
.LBB0_165:
	s_add_i32 s44, s18, 2
	s_add_u32 s20, s16, 0x80
	s_addc_u32 s19, s17, 0
	s_add_i32 s45, 0, 0x10000
	v_add_u32_e32 v142, s45, v146
	ds_read_b128 v[138:141], v142
	ds_read_b128 v[152:155], v142 offset:1024
	ds_read_b128 v[156:159], v142 offset:2048
	ds_read_b128 v[160:163], v142 offset:3072
	s_cmp_eq_u32 s35, s18
	s_cselect_b32 s18, s10, s20
	s_cselect_b32 s19, s11, s19
	s_cselect_b32 s21, s13, s43
	s_cselect_b32 s20, s12, s42
	v_lshl_add_u64 v[142:143], s[16:17], 0, v[136:137]
	s_add_i32 m0, s27, 0xc000
	ds_read_b128 v[164:167], v150
	ds_read_b128 v[168:171], v150 offset:1024
	ds_read_b128 v[172:175], v150 offset:2048
	ds_read_b128 v[176:179], v150 offset:3072
	ds_read_b128 v[180:183], v150 offset:4096
	ds_read_b128 v[184:187], v150 offset:5120
	ds_read_b128 v[188:191], v150 offset:6144
	ds_read_b128 v[202:205], v150 offset:7168
	global_load_lds_dwordx4 v[142:143], off
	v_lshl_add_u64 v[142:143], s[16:17], 0, v[134:135]
	s_add_i32 m0, s27, 0xe000
	s_nop 0
	global_load_lds_dwordx4 v[142:143], off
	s_waitcnt lgkmcnt(8)
	s_barrier
	s_waitcnt lgkmcnt(0)
	s_waitcnt lgkmcnt(0)
	v_mfma_f32_16x16x32_bf16 v[124:127], v[138:141], v[164:167], v[124:127]
	v_mfma_f32_16x16x32_bf16 v[120:123], v[156:159], v[164:167], v[120:123]
	v_mfma_f32_16x16x32_bf16 v[108:111], v[138:141], v[172:175], v[108:111]
	v_mfma_f32_16x16x32_bf16 v[104:107], v[156:159], v[172:175], v[104:107]
	v_mfma_f32_16x16x32_bf16 v[92:95], v[138:141], v[180:183], v[92:95]
	v_mfma_f32_16x16x32_bf16 v[88:91], v[156:159], v[180:183], v[88:91]
	v_mfma_f32_16x16x32_bf16 v[76:79], v[138:141], v[188:191], v[76:79]
	v_mfma_f32_16x16x32_bf16 v[72:75], v[156:159], v[188:191], v[72:75]
	v_mfma_f32_16x16x32_bf16 v[124:127], v[152:155], v[168:171], v[124:127]
	v_mfma_f32_16x16x32_bf16 v[120:123], v[160:163], v[168:171], v[120:123]
	v_mfma_f32_16x16x32_bf16 v[108:111], v[152:155], v[176:179], v[108:111]
	v_mfma_f32_16x16x32_bf16 v[104:107], v[160:163], v[176:179], v[104:107]
	v_mfma_f32_16x16x32_bf16 v[92:95], v[152:155], v[184:187], v[92:95]
	v_mfma_f32_16x16x32_bf16 v[88:91], v[160:163], v[184:187], v[88:91]
	v_mfma_f32_16x16x32_bf16 v[76:79], v[152:155], v[202:205], v[76:79]
	v_mfma_f32_16x16x32_bf16 v[72:75], v[160:163], v[202:205], v[72:75]
	s_barrier
	s_add_i32 s46, 0, 0x14000
	v_add_u32_e32 v142, s46, v146
	s_add_i32 s45, s45, s26
	ds_read_b128 v[206:209], v142
	ds_read_b128 v[210:213], v142 offset:1024
	ds_read_b128 v[214:217], v142 offset:2048
	ds_read_b128 v[218:221], v142 offset:3072
	v_lshl_add_u64 v[142:143], s[20:21], 0, v[194:195]
	s_mov_b32 m0, s45
	v_lshl_add_u64 v[222:223], s[20:21], 0, v[132:133]
	global_load_lds_dwordx4 v[142:143], off
	s_add_i32 m0, s45, 0x2000
	s_nop 0
	global_load_lds_dwordx4 v[222:223], off
	s_barrier
	s_waitcnt lgkmcnt(0)
	s_waitcnt lgkmcnt(0)
	v_mfma_f32_16x16x32_bf16 v[116:119], v[206:209], v[164:167], v[116:119]
	v_mfma_f32_16x16x32_bf16 v[112:115], v[214:217], v[164:167], v[112:115]
	v_mfma_f32_16x16x32_bf16 v[100:103], v[206:209], v[172:175], v[100:103]
	v_mfma_f32_16x16x32_bf16 v[96:99], v[214:217], v[172:175], v[96:99]
	v_mfma_f32_16x16x32_bf16 v[84:87], v[206:209], v[180:183], v[84:87]
	v_mfma_f32_16x16x32_bf16 v[80:83], v[214:217], v[180:183], v[80:83]
	v_mfma_f32_16x16x32_bf16 v[68:71], v[206:209], v[188:191], v[68:71]
	v_mfma_f32_16x16x32_bf16 v[64:67], v[214:217], v[188:191], v[64:67]
	v_mfma_f32_16x16x32_bf16 v[116:119], v[210:213], v[168:171], v[116:119]
	v_mfma_f32_16x16x32_bf16 v[112:115], v[218:221], v[168:171], v[112:115]
	v_mfma_f32_16x16x32_bf16 v[100:103], v[210:213], v[176:179], v[100:103]
	v_mfma_f32_16x16x32_bf16 v[96:99], v[218:221], v[176:179], v[96:99]
	v_mfma_f32_16x16x32_bf16 v[84:87], v[210:213], v[184:187], v[84:87]
	v_mfma_f32_16x16x32_bf16 v[80:83], v[218:221], v[184:187], v[80:83]
	v_mfma_f32_16x16x32_bf16 v[68:71], v[210:213], v[202:205], v[68:71]
	v_mfma_f32_16x16x32_bf16 v[64:67], v[218:221], v[202:205], v[64:67]
	s_mov_b32 m0, s27
	v_lshl_add_u64 v[224:225], s[18:19], 0, v[128:129]
	s_barrier
	ds_read_b128 v[164:167], v150 offset:16384
	ds_read_b128 v[168:171], v150 offset:17408
	ds_read_b128 v[172:175], v150 offset:18432
	ds_read_b128 v[176:179], v150 offset:19456
	ds_read_b128 v[180:183], v150 offset:20480
	ds_read_b128 v[184:187], v150 offset:21504
	ds_read_b128 v[188:191], v150 offset:22528
	ds_read_b128 v[202:205], v150 offset:23552
	global_load_lds_dwordx4 v[224:225], off
	v_lshl_add_u64 v[226:227], s[18:19], 0, v[130:131]
	s_mov_b32 m0, s28
	s_nop 0
	global_load_lds_dwordx4 v[226:227], off
	s_barrier
	s_waitcnt lgkmcnt(0)
	s_waitcnt lgkmcnt(0)
	v_mfma_f32_16x16x32_bf16 v[60:63], v[138:141], v[164:167], v[60:63]
	v_mfma_f32_16x16x32_bf16 v[56:59], v[156:159], v[164:167], v[56:59]
	v_mfma_f32_16x16x32_bf16 v[44:47], v[138:141], v[172:175], v[44:47]
	v_mfma_f32_16x16x32_bf16 v[40:43], v[156:159], v[172:175], v[40:43]
	v_mfma_f32_16x16x32_bf16 v[28:31], v[138:141], v[180:183], v[28:31]
	v_mfma_f32_16x16x32_bf16 v[24:27], v[156:159], v[180:183], v[24:27]
	v_mfma_f32_16x16x32_bf16 v[12:15], v[138:141], v[188:191], v[12:15]
	v_mfma_f32_16x16x32_bf16 v[8:11], v[156:159], v[188:191], v[8:11]
	v_mfma_f32_16x16x32_bf16 v[60:63], v[152:155], v[168:171], v[60:63]
	v_mfma_f32_16x16x32_bf16 v[56:59], v[160:163], v[168:171], v[56:59]
	v_mfma_f32_16x16x32_bf16 v[44:47], v[152:155], v[176:179], v[44:47]
	v_mfma_f32_16x16x32_bf16 v[40:43], v[160:163], v[176:179], v[40:43]
	v_mfma_f32_16x16x32_bf16 v[28:31], v[152:155], v[184:187], v[28:31]
	v_mfma_f32_16x16x32_bf16 v[24:27], v[160:163], v[184:187], v[24:27]
	v_mfma_f32_16x16x32_bf16 v[12:15], v[152:155], v[202:205], v[12:15]
	v_mfma_f32_16x16x32_bf16 v[8:11], v[160:163], v[202:205], v[8:11]
	s_barrier
; #define PG8_STAGE(bufoff, gbase, voff) do { _Pragma("unroll") for (int _i = 0; _i < 2; ++_i) \
;         __builtin_amdgcn_global_load_lds((const unsigned*)((const char*)(gbase) + (voff)[_i]), (LAS unsigned*)(lds + (bufoff) + ldsw + _i * 8192), 16, 0, 0); } while (0)
; #define PG8_LDA(dst, b, h) do { _Pragma("unroll") for (int m = 0; m < 4; ++m) _Pragma("unroll") for (int k = 0; k < 2; ++k) dst[m][k] = *(const LAS bf16x8*)(lds + PG8_SA(b, h) + aoff + m * 2048 + k * 1024); } while (0)
; #define PG8_LDB(dst, b, h) do { _Pragma("unroll") for (int n = 0; n < 2; ++n) _Pragma("unroll") for (int k = 0; k < 2; ++k) dst[n][k] = *(const LAS bf16x8*)(lds + PG8_SB(b, h) + boff + n * 2048 + k * 1024); } while (0)
; #define PG8_MMA(ai, bj, At, Bt) do { __builtin_amdgcn_s_setprio(1); _Pragma("unroll") for (int m = 0; m < 4; ++m) _Pragma("unroll") for (int n = 0; n < 2; ++n) _Pragma("unroll") for (int k = 0; k < 2; ++k) \
;         acc[ai][bj][m][n] = __builtin_amdgcn_mfma_f32_16x16x32_bf16(Bt[n][k], At[m][k], acc[ai][bj][m][n], 0, 0, 0); __builtin_amdgcn_s_setprio(0); } while (0)
; #define PG8_WAIT_V(n) asm volatile("s_waitcnt vmcnt(" #n ")" ::: "memory")
; #define PG8_WAIT_L(n) asm volatile("s_waitcnt lgkmcnt(" #n ")" ::: "memory")
; #define PG8_BAR __builtin_amdgcn_s_barrier()
; #define PG8_SCHED __builtin_amdgcn_sched_barrier(0)
; template <class Epi>
; __device__ __forceinline__ void gemm_phase(LAS unsigned char* lds, const Gemm g, const StaticOrder& S, const Epi& E) {
;     ...
;             PG8_STAGE(PG8_SB(0, 1), b2 + hstep, voffB);
;             PG8_WAIT_V(6); PG8_BAR; PG8_MMA(1, 1, At, B1); PG8_BAR;
;             PG8_LDB(B0, 1, 0); PG8_SCHED; PG8_LDA(At, 1, 0); PG8_STAGE(PG8_SA(0, 1), a2 + hstep, voffA);
;             PG8_WAIT_L(8); PG8_BAR; PG8_WAIT_L(0); PG8_MMA(0, 0, At, B0); PG8_BAR; PG8_SCHED;
;             PG8_LDB(B1, 1, 1); PG8_STAGE(PG8_SB(1, 0), b3, voffB);
;             PG8_BAR; PG8_WAIT_L(0); PG8_MMA(0, 1, At, B1); PG8_BAR;
	s_add_u32 s20, s20, s2
	s_addc_u32 s21, s21, s3
	s_add_i32 s45, s46, s26
	v_lshl_add_u64 v[228:229], s[20:21], 0, v[194:195]
	s_mov_b32 m0, s45
	v_lshl_add_u64 v[230:231], s[20:21], 0, v[132:133]
	global_load_lds_dwordx4 v[228:229], off
	s_add_i32 m0, s45, 0x2000
	s_nop 0
	global_load_lds_dwordx4 v[230:231], off
	s_waitcnt vmcnt(6)
	s_barrier
	v_mfma_f32_16x16x32_bf16 v[52:55], v[206:209], v[164:167], v[52:55]
	v_mfma_f32_16x16x32_bf16 v[48:51], v[214:217], v[164:167], v[48:51]
	v_mfma_f32_16x16x32_bf16 v[36:39], v[206:209], v[172:175], v[36:39]
	v_mfma_f32_16x16x32_bf16 v[32:35], v[214:217], v[172:175], v[32:35]
	v_mfma_f32_16x16x32_bf16 v[20:23], v[206:209], v[180:183], v[20:23]
	v_mfma_f32_16x16x32_bf16 v[16:19], v[214:217], v[180:183], v[16:19]
	v_mfma_f32_16x16x32_bf16 v[4:7], v[206:209], v[188:191], v[4:7]
	v_mfma_f32_16x16x32_bf16 v[0:3], v[214:217], v[188:191], v[0:3]
	v_mfma_f32_16x16x32_bf16 v[52:55], v[210:213], v[168:171], v[52:55]
	v_mfma_f32_16x16x32_bf16 v[48:51], v[218:221], v[168:171], v[48:51]
	v_mfma_f32_16x16x32_bf16 v[36:39], v[210:213], v[176:179], v[36:39]
	v_mfma_f32_16x16x32_bf16 v[32:35], v[218:221], v[176:179], v[32:35]
	v_mfma_f32_16x16x32_bf16 v[20:23], v[210:213], v[184:187], v[20:23]
	v_mfma_f32_16x16x32_bf16 v[16:19], v[218:221], v[184:187], v[16:19]
	v_mfma_f32_16x16x32_bf16 v[4:7], v[210:213], v[202:205], v[4:7]
	v_mfma_f32_16x16x32_bf16 v[0:3], v[218:221], v[202:205], v[0:3]
	s_add_i32 s20, 0, 0x18000
	v_add_u32_e32 v151, s20, v146
	s_barrier
	ds_read_b128 v[138:141], v151
	ds_read_b128 v[152:155], v151 offset:1024
	ds_read_b128 v[156:159], v151 offset:2048
	ds_read_b128 v[160:163], v151 offset:3072
	s_add_u32 s18, s18, s2
	s_addc_u32 s19, s19, s3
	s_mov_b32 m0, s29
	v_lshl_add_u64 v[206:207], s[18:19], 0, v[128:129]
	ds_read_b128 v[164:167], v150 offset:32768
	ds_read_b128 v[168:171], v150 offset:33792
	ds_read_b128 v[172:175], v150 offset:34816
	ds_read_b128 v[176:179], v150 offset:35840
	ds_read_b128 v[180:183], v150 offset:36864
	ds_read_b128 v[184:187], v150 offset:37888
	ds_read_b128 v[188:191], v150 offset:38912
	ds_read_b128 v[202:205], v150 offset:39936
	global_load_lds_dwordx4 v[206:207], off
	v_lshl_add_u64 v[206:207], s[18:19], 0, v[130:131]
	s_mov_b32 m0, s30
	s_nop 0
	global_load_lds_dwordx4 v[206:207], off
	s_waitcnt lgkmcnt(8)
	s_barrier
	s_waitcnt lgkmcnt(0)
	s_waitcnt lgkmcnt(0)
	v_mfma_f32_16x16x32_bf16 v[124:127], v[138:141], v[164:167], v[124:127]
	v_mfma_f32_16x16x32_bf16 v[120:123], v[156:159], v[164:167], v[120:123]
	v_mfma_f32_16x16x32_bf16 v[108:111], v[138:141], v[172:175], v[108:111]
	v_mfma_f32_16x16x32_bf16 v[104:107], v[156:159], v[172:175], v[104:107]
	v_mfma_f32_16x16x32_bf16 v[92:95], v[138:141], v[180:183], v[92:95]
	v_mfma_f32_16x16x32_bf16 v[88:91], v[156:159], v[180:183], v[88:91]
	v_mfma_f32_16x16x32_bf16 v[76:79], v[138:141], v[188:191], v[76:79]
	v_mfma_f32_16x16x32_bf16 v[72:75], v[156:159], v[188:191], v[72:75]
	v_mfma_f32_16x16x32_bf16 v[124:127], v[152:155], v[168:171], v[124:127]
	v_mfma_f32_16x16x32_bf16 v[120:123], v[160:163], v[168:171], v[120:123]
	v_mfma_f32_16x16x32_bf16 v[108:111], v[152:155], v[176:179], v[108:111]
	v_mfma_f32_16x16x32_bf16 v[104:107], v[160:163], v[176:179], v[104:107]
	v_mfma_f32_16x16x32_bf16 v[92:95], v[152:155], v[184:187], v[92:95]
	v_mfma_f32_16x16x32_bf16 v[88:91], v[160:163], v[184:187], v[88:91]
	v_mfma_f32_16x16x32_bf16 v[76:79], v[152:155], v[202:205], v[76:79]
	v_mfma_f32_16x16x32_bf16 v[72:75], v[160:163], v[202:205], v[72:75]
	s_barrier
	s_add_i32 s18, 0, 0x1c000
	s_add_i32 s19, s20, s26
	v_add_u32_e32 v151, s18, v146
	v_lshl_add_u64 v[142:143], v[142:143], 0, s[48:49]
	s_mov_b32 m0, s19
	ds_read_b128 v[206:209], v151
	ds_read_b128 v[210:213], v151 offset:1024
	ds_read_b128 v[214:217], v151 offset:2048
	ds_read_b128 v[218:221], v151 offset:3072
	global_load_lds_dwordx4 v[142:143], off
	v_lshl_add_u64 v[142:143], v[222:223], 0, s[48:49]
	s_add_i32 m0, s19, 0x2000
	s_nop 0
	global_load_lds_dwordx4 v[142:143], off
	s_barrier
; #define PG8_STAGE(bufoff, gbase, voff) do { _Pragma("unroll") for (int _i = 0; _i < 2; ++_i) \
;         __builtin_amdgcn_global_load_lds((const unsigned*)((const char*)(gbase) + (voff)[_i]), (LAS unsigned*)(lds + (bufoff) + ldsw + _i * 8192), 16, 0, 0); } while (0)
; #define PG8_LDA(dst, b, h) do { _Pragma("unroll") for (int m = 0; m < 4; ++m) _Pragma("unroll") for (int k = 0; k < 2; ++k) dst[m][k] = *(const LAS bf16x8*)(lds + PG8_SA(b, h) + aoff + m * 2048 + k * 1024); } while (0)
; #define PG8_MMA(ai, bj, At, Bt) do { __builtin_amdgcn_s_setprio(1); _Pragma("unroll") for (int m = 0; m < 4; ++m) _Pragma("unroll") for (int n = 0; n < 2; ++n) _Pragma("unroll") for (int k = 0; k < 2; ++k) \
;         acc[ai][bj][m][n] = __builtin_amdgcn_mfma_f32_16x16x32_bf16(Bt[n][k], At[m][k], acc[ai][bj][m][n], 0, 0, 0); __builtin_amdgcn_s_setprio(0); } while (0)
; #define PG8_WAIT_V(n) asm volatile("s_waitcnt vmcnt(" #n ")" ::: "memory")
; #define PG8_WAIT_L(n) asm volatile("s_waitcnt lgkmcnt(" #n ")" ::: "memory")
; #define PG8_BAR __builtin_amdgcn_s_barrier()
; #define PG8_SCHED __builtin_amdgcn_sched_barrier(0)
; template <class Epi>
; __device__ __forceinline__ void gemm_phase(LAS unsigned char* lds, const Gemm g, const StaticOrder& S, const Epi& E) {
;     ...
;             PG8_BAR; PG8_WAIT_L(0); PG8_MMA(0, 1, At, B1); PG8_BAR;
;             PG8_LDA(At, 1, 1); PG8_STAGE(PG8_SA(1, 0), a3, voffA);
;             PG8_BAR; PG8_WAIT_L(0); PG8_MMA(1, 0, At, B0); PG8_BAR; PG8_SCHED;
;             PG8_STAGE(PG8_SB(1, 1), b3 + hstep, voffB);
;             PG8_WAIT_V(6); PG8_BAR; PG8_MMA(1, 1, At, B1); PG8_BAR;
;         }
	s_waitcnt lgkmcnt(0)
	s_waitcnt lgkmcnt(0)
	v_mfma_f32_16x16x32_bf16 v[116:119], v[206:209], v[164:167], v[116:119]
	v_mfma_f32_16x16x32_bf16 v[112:115], v[214:217], v[164:167], v[112:115]
	v_mfma_f32_16x16x32_bf16 v[100:103], v[206:209], v[172:175], v[100:103]
	v_mfma_f32_16x16x32_bf16 v[96:99], v[214:217], v[172:175], v[96:99]
	v_mfma_f32_16x16x32_bf16 v[84:87], v[206:209], v[180:183], v[84:87]
	v_mfma_f32_16x16x32_bf16 v[80:83], v[214:217], v[180:183], v[80:83]
	v_mfma_f32_16x16x32_bf16 v[68:71], v[206:209], v[188:191], v[68:71]
	v_mfma_f32_16x16x32_bf16 v[64:67], v[214:217], v[188:191], v[64:67]
	v_mfma_f32_16x16x32_bf16 v[116:119], v[210:213], v[168:171], v[116:119]
	v_mfma_f32_16x16x32_bf16 v[112:115], v[218:221], v[168:171], v[112:115]
	v_mfma_f32_16x16x32_bf16 v[100:103], v[210:213], v[176:179], v[100:103]
	v_mfma_f32_16x16x32_bf16 v[96:99], v[218:221], v[176:179], v[96:99]
	v_mfma_f32_16x16x32_bf16 v[84:87], v[210:213], v[184:187], v[84:87]
	v_mfma_f32_16x16x32_bf16 v[80:83], v[218:221], v[184:187], v[80:83]
	v_mfma_f32_16x16x32_bf16 v[68:71], v[210:213], v[202:205], v[68:71]
	v_mfma_f32_16x16x32_bf16 v[64:67], v[218:221], v[202:205], v[64:67]
	s_mov_b32 m0, s31
	v_lshl_add_u64 v[142:143], v[224:225], 0, s[48:49]
	s_barrier
	ds_read_b128 v[164:167], v150 offset:49152
	ds_read_b128 v[168:171], v150 offset:50176
	ds_read_b128 v[172:175], v150 offset:51200
	ds_read_b128 v[176:179], v150 offset:52224
	ds_read_b128 v[180:183], v150 offset:53248
	ds_read_b128 v[184:187], v150 offset:54272
	ds_read_b128 v[188:191], v150 offset:55296
	ds_read_b128 v[202:205], v150 offset:56320
	global_load_lds_dwordx4 v[142:143], off
	v_lshl_add_u64 v[142:143], v[226:227], 0, s[48:49]
	s_mov_b32 m0, s33
	s_nop 0
	global_load_lds_dwordx4 v[142:143], off
	s_barrier
	s_waitcnt lgkmcnt(0)
	s_waitcnt lgkmcnt(0)
	v_mfma_f32_16x16x32_bf16 v[60:63], v[138:141], v[164:167], v[60:63]
	v_mfma_f32_16x16x32_bf16 v[56:59], v[156:159], v[164:167], v[56:59]
	v_mfma_f32_16x16x32_bf16 v[44:47], v[138:141], v[172:175], v[44:47]
	v_mfma_f32_16x16x32_bf16 v[40:43], v[156:159], v[172:175], v[40:43]
	v_mfma_f32_16x16x32_bf16 v[28:31], v[138:141], v[180:183], v[28:31]
	v_mfma_f32_16x16x32_bf16 v[24:27], v[156:159], v[180:183], v[24:27]
	v_mfma_f32_16x16x32_bf16 v[12:15], v[138:141], v[188:191], v[12:15]
	v_mfma_f32_16x16x32_bf16 v[8:11], v[156:159], v[188:191], v[8:11]
	v_mfma_f32_16x16x32_bf16 v[60:63], v[152:155], v[168:171], v[60:63]
	v_mfma_f32_16x16x32_bf16 v[56:59], v[160:163], v[168:171], v[56:59]
	v_mfma_f32_16x16x32_bf16 v[44:47], v[152:155], v[176:179], v[44:47]
	v_mfma_f32_16x16x32_bf16 v[40:43], v[160:163], v[176:179], v[40:43]
	v_mfma_f32_16x16x32_bf16 v[28:31], v[152:155], v[184:187], v[28:31]
	v_mfma_f32_16x16x32_bf16 v[24:27], v[160:163], v[184:187], v[24:27]
	v_mfma_f32_16x16x32_bf16 v[12:15], v[152:155], v[202:205], v[12:15]
	v_mfma_f32_16x16x32_bf16 v[8:11], v[160:163], v[202:205], v[8:11]
	s_barrier
	s_add_i32 s18, s18, s26
	v_lshl_add_u64 v[138:139], v[228:229], 0, s[48:49]
	s_mov_b32 m0, s18
	s_nop 0
	global_load_lds_dwordx4 v[138:139], off
	v_lshl_add_u64 v[138:139], v[230:231], 0, s[48:49]
	s_add_i32 m0, s18, 0x2000
	s_nop 0
	global_load_lds_dwordx4 v[138:139], off
	s_waitcnt vmcnt(6)
	s_barrier
	v_mfma_f32_16x16x32_bf16 v[52:55], v[206:209], v[164:167], v[52:55]
	v_mfma_f32_16x16x32_bf16 v[48:51], v[214:217], v[164:167], v[48:51]
	v_mfma_f32_16x16x32_bf16 v[36:39], v[206:209], v[172:175], v[36:39]
	v_mfma_f32_16x16x32_bf16 v[32:35], v[214:217], v[172:175], v[32:35]
	v_mfma_f32_16x16x32_bf16 v[20:23], v[206:209], v[180:183], v[20:23]
	v_mfma_f32_16x16x32_bf16 v[16:19], v[214:217], v[180:183], v[16:19]
	v_mfma_f32_16x16x32_bf16 v[4:7], v[206:209], v[188:191], v[4:7]
	v_mfma_f32_16x16x32_bf16 v[0:3], v[214:217], v[188:191], v[0:3]
	v_mfma_f32_16x16x32_bf16 v[52:55], v[210:213], v[168:171], v[52:55]
	v_mfma_f32_16x16x32_bf16 v[48:51], v[218:221], v[168:171], v[48:51]
	v_mfma_f32_16x16x32_bf16 v[36:39], v[210:213], v[176:179], v[36:39]
	v_mfma_f32_16x16x32_bf16 v[32:35], v[218:221], v[176:179], v[32:35]
	v_mfma_f32_16x16x32_bf16 v[20:23], v[210:213], v[184:187], v[20:23]
	v_mfma_f32_16x16x32_bf16 v[16:19], v[218:221], v[184:187], v[16:19]
	v_mfma_f32_16x16x32_bf16 v[4:7], v[210:213], v[202:205], v[4:7]
	v_mfma_f32_16x16x32_bf16 v[0:3], v[218:221], v[202:205], v[0:3]
	s_add_u32 s42, s42, 0x100
	s_addc_u32 s43, s43, 0
	s_add_u32 s16, s16, 0x100
	s_addc_u32 s17, s17, 0
	s_cmp_ge_i32 s44, s34
	s_mov_b32 s18, s44
	s_barrier
	s_cbranch_scc0 .LBB0_165

; #define PG8_STAGE(bufoff, gbase, voff) do { _Pragma("unroll") for (int _i = 0; _i < 2; ++_i) \
;         __builtin_amdgcn_global_load_lds((const unsigned*)((const char*)(gbase) + (voff)[_i]), (LAS unsigned*)(lds + (bufoff) + ldsw + _i * 8192), 16, 0, 0); } while (0)
; #define PG8_LDA(dst, b, h) do { _Pragma("unroll") for (int m = 0; m < 4; ++m) _Pragma("unroll") for (int k = 0; k < 2; ++k) dst[m][k] = *(const LAS bf16x8*)(lds + PG8_SA(b, h) + aoff + m * 2048 + k * 1024); } while (0)
; #define PG8_LDB(dst, b, h) do { _Pragma("unroll") for (int n = 0; n < 2; ++n) _Pragma("unroll") for (int k = 0; k < 2; ++k) dst[n][k] = *(const LAS bf16x8*)(lds + PG8_SB(b, h) + boff + n * 2048 + k * 1024); } while (0)
; #define PG8_MMA(ai, bj, At, Bt) do { __builtin_amdgcn_s_setprio(1); _Pragma("unroll") for (int m = 0; m < 4; ++m) _Pragma("unroll") for (int n = 0; n < 2; ++n) _Pragma("unroll") for (int k = 0; k < 2; ++k) \
;         acc[ai][bj][m][n] = __builtin_amdgcn_mfma_f32_16x16x32_bf16(Bt[n][k], At[m][k], acc[ai][bj][m][n], 0, 0, 0); __builtin_amdgcn_s_setprio(0); } while (0)
; #define PG8_WAIT_L(n) asm volatile("s_waitcnt lgkmcnt(" #n ")" ::: "memory")
; #define PG8_BAR __builtin_amdgcn_s_barrier()
; #define PG8_SCHED __builtin_amdgcn_sched_barrier(0)
; template <class Epi>
; __device__ __forceinline__ void gemm_phase(LAS unsigned char* lds, const Gemm g, const StaticOrder& S, const Epi& E) {
;     ...
;         for (int t = 0; t < nt; t += 2) {
;             const bool last = (t == nt - 2);
;             const char* a1 = cA + (size_t)(t + 1) * kstep;
;             const char* a2 = last ? nA : cA + (size_t)(t + 2) * kstep; const char* b2 = last ? nB : cB + (size_t)(t + 2) * kstep;
;             const char* a3 = a2 + kstep; const char* b3 = b2 + kstep;
;             PG8_LDB(B0, 0, 0); PG8_SCHED; PG8_LDA(At, 0, 0); PG8_STAGE(PG8_SA(1, 1), a1 + hstep, voffA);
;             PG8_WAIT_L(8); PG8_BAR; PG8_WAIT_L(0); PG8_MMA(0, 0, At, B0); PG8_BAR; PG8_SCHED;
;             PG8_LDB(B1, 0, 1); PG8_STAGE(PG8_SB(0, 0), b2, voffB);
;             PG8_BAR; PG8_WAIT_L(0); PG8_MMA(0, 1, At, B1); PG8_BAR;
;             PG8_LDA(At, 0, 1); PG8_STAGE(PG8_SA(0, 0), a2, voffA);
;             PG8_BAR; PG8_WAIT_L(0); PG8_MMA(1, 0, At, B0); PG8_BAR; PG8_SCHED;
.LBB0_528:
	s_add_i32 s42, s18, 2
	s_add_u32 s20, s16, 0x80
	s_addc_u32 s19, s17, 0
	s_add_i32 s43, 0, 0x10000
	v_add_u32_e32 v149, s43, v144
	ds_read_b128 v[138:141], v149
	ds_read_b128 v[150:153], v149 offset:1024
	ds_read_b128 v[154:157], v149 offset:2048
	ds_read_b128 v[158:161], v149 offset:3072
	s_cmp_eq_u32 s33, s18
	s_cselect_b32 s18, s10, s20
	s_cselect_b32 s19, s11, s19
	s_cselect_b32 s21, s13, s41
	s_cselect_b32 s20, s12, s40
	v_lshl_add_u64 v[190:191], s[16:17], 0, v[136:137]
	s_add_i32 m0, s25, 0xc000
	ds_read_b128 v[162:165], v148
	ds_read_b128 v[166:169], v148 offset:1024
	ds_read_b128 v[170:173], v148 offset:2048
	ds_read_b128 v[174:177], v148 offset:3072
	ds_read_b128 v[178:181], v148 offset:4096
	ds_read_b128 v[182:185], v148 offset:5120
	ds_read_b128 v[186:189], v148 offset:6144
	ds_read_b128 v[202:205], v148 offset:7168
	global_load_lds_dwordx4 v[190:191], off
	v_lshl_add_u64 v[190:191], s[16:17], 0, v[134:135]
	s_add_i32 m0, s25, 0xe000
	s_nop 0
	global_load_lds_dwordx4 v[190:191], off
	s_waitcnt lgkmcnt(8)
	s_barrier
	s_waitcnt lgkmcnt(0)
	s_waitcnt lgkmcnt(0)
	v_mfma_f32_16x16x32_bf16 v[124:127], v[138:141], v[162:165], v[124:127]
	v_mfma_f32_16x16x32_bf16 v[120:123], v[154:157], v[162:165], v[120:123]
	v_mfma_f32_16x16x32_bf16 v[108:111], v[138:141], v[170:173], v[108:111]
	v_mfma_f32_16x16x32_bf16 v[104:107], v[154:157], v[170:173], v[104:107]
	v_mfma_f32_16x16x32_bf16 v[92:95], v[138:141], v[178:181], v[92:95]
	v_mfma_f32_16x16x32_bf16 v[88:91], v[154:157], v[178:181], v[88:91]
	v_mfma_f32_16x16x32_bf16 v[76:79], v[138:141], v[186:189], v[76:79]
	v_mfma_f32_16x16x32_bf16 v[72:75], v[154:157], v[186:189], v[72:75]
	v_mfma_f32_16x16x32_bf16 v[124:127], v[150:153], v[166:169], v[124:127]
	v_mfma_f32_16x16x32_bf16 v[120:123], v[158:161], v[166:169], v[120:123]
	v_mfma_f32_16x16x32_bf16 v[108:111], v[150:153], v[174:177], v[108:111]
	v_mfma_f32_16x16x32_bf16 v[104:107], v[158:161], v[174:177], v[104:107]
	v_mfma_f32_16x16x32_bf16 v[92:95], v[150:153], v[182:185], v[92:95]
	v_mfma_f32_16x16x32_bf16 v[88:91], v[158:161], v[182:185], v[88:91]
	v_mfma_f32_16x16x32_bf16 v[76:79], v[150:153], v[202:205], v[76:79]
	v_mfma_f32_16x16x32_bf16 v[72:75], v[158:161], v[202:205], v[72:75]
	s_barrier
	s_add_i32 s44, 0, 0x14000
	s_add_i32 s43, s43, s24
	v_add_u32_e32 v149, s44, v144
	v_lshl_add_u64 v[190:191], s[20:21], 0, v[194:195]
	s_mov_b32 m0, s43
	ds_read_b128 v[206:209], v149
	ds_read_b128 v[210:213], v149 offset:1024
	ds_read_b128 v[214:217], v149 offset:2048
	ds_read_b128 v[218:221], v149 offset:3072
	global_load_lds_dwordx4 v[190:191], off
	v_lshl_add_u64 v[222:223], s[20:21], 0, v[132:133]
	s_add_i32 m0, s43, 0x2000
	s_nop 0
	global_load_lds_dwordx4 v[222:223], off
	s_barrier
	s_waitcnt lgkmcnt(0)
	s_waitcnt lgkmcnt(0)
	v_mfma_f32_16x16x32_bf16 v[116:119], v[206:209], v[162:165], v[116:119]
	v_mfma_f32_16x16x32_bf16 v[112:115], v[214:217], v[162:165], v[112:115]
	v_mfma_f32_16x16x32_bf16 v[100:103], v[206:209], v[170:173], v[100:103]
	v_mfma_f32_16x16x32_bf16 v[96:99], v[214:217], v[170:173], v[96:99]
	v_mfma_f32_16x16x32_bf16 v[84:87], v[206:209], v[178:181], v[84:87]
	v_mfma_f32_16x16x32_bf16 v[80:83], v[214:217], v[178:181], v[80:83]
	v_mfma_f32_16x16x32_bf16 v[68:71], v[206:209], v[186:189], v[68:71]
	v_mfma_f32_16x16x32_bf16 v[64:67], v[214:217], v[186:189], v[64:67]
	v_mfma_f32_16x16x32_bf16 v[116:119], v[210:213], v[166:169], v[116:119]
	v_mfma_f32_16x16x32_bf16 v[112:115], v[218:221], v[166:169], v[112:115]
	v_mfma_f32_16x16x32_bf16 v[100:103], v[210:213], v[174:177], v[100:103]
	v_mfma_f32_16x16x32_bf16 v[96:99], v[218:221], v[174:177], v[96:99]
	v_mfma_f32_16x16x32_bf16 v[84:87], v[210:213], v[182:185], v[84:87]
	v_mfma_f32_16x16x32_bf16 v[80:83], v[218:221], v[182:185], v[80:83]
	v_mfma_f32_16x16x32_bf16 v[68:71], v[210:213], v[202:205], v[68:71]
	v_mfma_f32_16x16x32_bf16 v[64:67], v[218:221], v[202:205], v[64:67]
	s_mov_b32 m0, s25
	v_lshl_add_u64 v[224:225], s[18:19], 0, v[128:129]
	s_barrier
	ds_read_b128 v[162:165], v148 offset:16384
	ds_read_b128 v[166:169], v148 offset:17408
	ds_read_b128 v[170:173], v148 offset:18432
	ds_read_b128 v[174:177], v148 offset:19456
	ds_read_b128 v[178:181], v148 offset:20480
	ds_read_b128 v[182:185], v148 offset:21504
	ds_read_b128 v[186:189], v148 offset:22528
	ds_read_b128 v[202:205], v148 offset:23552
	global_load_lds_dwordx4 v[224:225], off
	v_lshl_add_u64 v[226:227], s[18:19], 0, v[130:131]
	s_mov_b32 m0, s26
	s_nop 0
	global_load_lds_dwordx4 v[226:227], off
	s_barrier
	s_waitcnt lgkmcnt(0)
	s_waitcnt lgkmcnt(0)
	v_mfma_f32_16x16x32_bf16 v[60:63], v[138:141], v[162:165], v[60:63]
	v_mfma_f32_16x16x32_bf16 v[56:59], v[154:157], v[162:165], v[56:59]
	v_mfma_f32_16x16x32_bf16 v[44:47], v[138:141], v[170:173], v[44:47]
	v_mfma_f32_16x16x32_bf16 v[40:43], v[154:157], v[170:173], v[40:43]
	v_mfma_f32_16x16x32_bf16 v[28:31], v[138:141], v[178:181], v[28:31]
	v_mfma_f32_16x16x32_bf16 v[24:27], v[154:157], v[178:181], v[24:27]
	v_mfma_f32_16x16x32_bf16 v[12:15], v[138:141], v[186:189], v[12:15]
	v_mfma_f32_16x16x32_bf16 v[8:11], v[154:157], v[186:189], v[8:11]
	v_mfma_f32_16x16x32_bf16 v[60:63], v[150:153], v[166:169], v[60:63]
	v_mfma_f32_16x16x32_bf16 v[56:59], v[158:161], v[166:169], v[56:59]
	v_mfma_f32_16x16x32_bf16 v[44:47], v[150:153], v[174:177], v[44:47]
	v_mfma_f32_16x16x32_bf16 v[40:43], v[158:161], v[174:177], v[40:43]
	v_mfma_f32_16x16x32_bf16 v[28:31], v[150:153], v[182:185], v[28:31]
	v_mfma_f32_16x16x32_bf16 v[24:27], v[158:161], v[182:185], v[24:27]
	v_mfma_f32_16x16x32_bf16 v[12:15], v[150:153], v[202:205], v[12:15]
	v_mfma_f32_16x16x32_bf16 v[8:11], v[158:161], v[202:205], v[8:11]
	s_barrier
; #define PG8_STAGE(bufoff, gbase, voff) do { _Pragma("unroll") for (int _i = 0; _i < 2; ++_i) \
;         __builtin_amdgcn_global_load_lds((const unsigned*)((const char*)(gbase) + (voff)[_i]), (LAS unsigned*)(lds + (bufoff) + ldsw + _i * 8192), 16, 0, 0); } while (0)
; #define PG8_LDA(dst, b, h) do { _Pragma("unroll") for (int m = 0; m < 4; ++m) _Pragma("unroll") for (int k = 0; k < 2; ++k) dst[m][k] = *(const LAS bf16x8*)(lds + PG8_SA(b, h) + aoff + m * 2048 + k * 1024); } while (0)
; #define PG8_LDB(dst, b, h) do { _Pragma("unroll") for (int n = 0; n < 2; ++n) _Pragma("unroll") for (int k = 0; k < 2; ++k) dst[n][k] = *(const LAS bf16x8*)(lds + PG8_SB(b, h) + boff + n * 2048 + k * 1024); } while (0)
; #define PG8_MMA(ai, bj, At, Bt) do { __builtin_amdgcn_s_setprio(1); _Pragma("unroll") for (int m = 0; m < 4; ++m) _Pragma("unroll") for (int n = 0; n < 2; ++n) _Pragma("unroll") for (int k = 0; k < 2; ++k) \
;         acc[ai][bj][m][n] = __builtin_amdgcn_mfma_f32_16x16x32_bf16(Bt[n][k], At[m][k], acc[ai][bj][m][n], 0, 0, 0); __builtin_amdgcn_s_setprio(0); } while (0)
; #define PG8_WAIT_V(n) asm volatile("s_waitcnt vmcnt(" #n ")" ::: "memory")
; #define PG8_WAIT_L(n) asm volatile("s_waitcnt lgkmcnt(" #n ")" ::: "memory")
; #define PG8_BAR __builtin_amdgcn_s_barrier()
; #define PG8_SCHED __builtin_amdgcn_sched_barrier(0)
; template <class Epi>
; __device__ __forceinline__ void gemm_phase(LAS unsigned char* lds, const Gemm g, const StaticOrder& S, const Epi& E) {
;     ...
;             PG8_STAGE(PG8_SB(0, 1), b2 + hstep, voffB);
;             PG8_WAIT_V(6); PG8_BAR; PG8_MMA(1, 1, At, B1); PG8_BAR;
;             PG8_LDB(B0, 1, 0); PG8_SCHED; PG8_LDA(At, 1, 0); PG8_STAGE(PG8_SA(0, 1), a2 + hstep, voffA);
;             PG8_WAIT_L(8); PG8_BAR; PG8_WAIT_L(0); PG8_MMA(0, 0, At, B0); PG8_BAR; PG8_SCHED;
;             PG8_LDB(B1, 1, 1); PG8_STAGE(PG8_SB(1, 0), b3, voffB);
;             PG8_BAR; PG8_WAIT_L(0); PG8_MMA(0, 1, At, B1); PG8_BAR;
	s_add_u32 s20, s20, s2
	s_addc_u32 s21, s21, s3
	s_add_i32 s43, s44, s24
	v_lshl_add_u64 v[228:229], s[20:21], 0, v[194:195]
	s_mov_b32 m0, s43
	v_lshl_add_u64 v[230:231], s[20:21], 0, v[132:133]
	global_load_lds_dwordx4 v[228:229], off
	s_add_i32 m0, s43, 0x2000
	s_nop 0
	global_load_lds_dwordx4 v[230:231], off
	s_waitcnt vmcnt(6)
	s_barrier
	v_mfma_f32_16x16x32_bf16 v[52:55], v[206:209], v[162:165], v[52:55]
	v_mfma_f32_16x16x32_bf16 v[48:51], v[214:217], v[162:165], v[48:51]
	v_mfma_f32_16x16x32_bf16 v[36:39], v[206:209], v[170:173], v[36:39]
	v_mfma_f32_16x16x32_bf16 v[32:35], v[214:217], v[170:173], v[32:35]
	v_mfma_f32_16x16x32_bf16 v[20:23], v[206:209], v[178:181], v[20:23]
	v_mfma_f32_16x16x32_bf16 v[16:19], v[214:217], v[178:181], v[16:19]
	v_mfma_f32_16x16x32_bf16 v[4:7], v[206:209], v[186:189], v[4:7]
	v_mfma_f32_16x16x32_bf16 v[0:3], v[214:217], v[186:189], v[0:3]
	v_mfma_f32_16x16x32_bf16 v[52:55], v[210:213], v[166:169], v[52:55]
	v_mfma_f32_16x16x32_bf16 v[48:51], v[218:221], v[166:169], v[48:51]
	v_mfma_f32_16x16x32_bf16 v[36:39], v[210:213], v[174:177], v[36:39]
	v_mfma_f32_16x16x32_bf16 v[32:35], v[218:221], v[174:177], v[32:35]
	v_mfma_f32_16x16x32_bf16 v[20:23], v[210:213], v[182:185], v[20:23]
	v_mfma_f32_16x16x32_bf16 v[16:19], v[218:221], v[182:185], v[16:19]
	v_mfma_f32_16x16x32_bf16 v[4:7], v[210:213], v[202:205], v[4:7]
	v_mfma_f32_16x16x32_bf16 v[0:3], v[218:221], v[202:205], v[0:3]
	s_add_i32 s20, 0, 0x18000
	v_add_u32_e32 v149, s20, v144
	s_barrier
	ds_read_b128 v[138:141], v149
	ds_read_b128 v[150:153], v149 offset:1024
	ds_read_b128 v[154:157], v149 offset:2048
	ds_read_b128 v[158:161], v149 offset:3072
	s_add_u32 s18, s18, s2
	s_addc_u32 s19, s19, s3
	s_mov_b32 m0, s27
	v_lshl_add_u64 v[206:207], s[18:19], 0, v[128:129]
	ds_read_b128 v[162:165], v148 offset:32768
	ds_read_b128 v[166:169], v148 offset:33792
	ds_read_b128 v[170:173], v148 offset:34816
	ds_read_b128 v[174:177], v148 offset:35840
	ds_read_b128 v[178:181], v148 offset:36864
	ds_read_b128 v[182:185], v148 offset:37888
	ds_read_b128 v[186:189], v148 offset:38912
	ds_read_b128 v[202:205], v148 offset:39936
	global_load_lds_dwordx4 v[206:207], off
	v_lshl_add_u64 v[206:207], s[18:19], 0, v[130:131]
	s_mov_b32 m0, s28
	s_nop 0
	global_load_lds_dwordx4 v[206:207], off
	s_waitcnt lgkmcnt(8)
	s_barrier
	s_waitcnt lgkmcnt(0)
	s_waitcnt lgkmcnt(0)
	v_mfma_f32_16x16x32_bf16 v[124:127], v[138:141], v[162:165], v[124:127]
	v_mfma_f32_16x16x32_bf16 v[120:123], v[154:157], v[162:165], v[120:123]
	v_mfma_f32_16x16x32_bf16 v[108:111], v[138:141], v[170:173], v[108:111]
	v_mfma_f32_16x16x32_bf16 v[104:107], v[154:157], v[170:173], v[104:107]
	v_mfma_f32_16x16x32_bf16 v[92:95], v[138:141], v[178:181], v[92:95]
	v_mfma_f32_16x16x32_bf16 v[88:91], v[154:157], v[178:181], v[88:91]
	v_mfma_f32_16x16x32_bf16 v[76:79], v[138:141], v[186:189], v[76:79]
	v_mfma_f32_16x16x32_bf16 v[72:75], v[154:157], v[186:189], v[72:75]
	v_mfma_f32_16x16x32_bf16 v[124:127], v[150:153], v[166:169], v[124:127]
	v_mfma_f32_16x16x32_bf16 v[120:123], v[158:161], v[166:169], v[120:123]
	v_mfma_f32_16x16x32_bf16 v[108:111], v[150:153], v[174:177], v[108:111]
	v_mfma_f32_16x16x32_bf16 v[104:107], v[158:161], v[174:177], v[104:107]
	v_mfma_f32_16x16x32_bf16 v[92:95], v[150:153], v[182:185], v[92:95]
	v_mfma_f32_16x16x32_bf16 v[88:91], v[158:161], v[182:185], v[88:91]
	v_mfma_f32_16x16x32_bf16 v[76:79], v[150:153], v[202:205], v[76:79]
	v_mfma_f32_16x16x32_bf16 v[72:75], v[158:161], v[202:205], v[72:75]
	s_barrier
	s_add_i32 s18, 0, 0x1c000
	s_add_i32 s19, s20, s24
	v_add_u32_e32 v149, s18, v144
	v_lshl_add_u64 v[190:191], v[190:191], 0, s[46:47]
	s_mov_b32 m0, s19
	ds_read_b128 v[206:209], v149
	ds_read_b128 v[210:213], v149 offset:1024
	ds_read_b128 v[214:217], v149 offset:2048
	ds_read_b128 v[218:221], v149 offset:3072
	global_load_lds_dwordx4 v[190:191], off
	v_lshl_add_u64 v[190:191], v[222:223], 0, s[46:47]
	s_add_i32 m0, s19, 0x2000
	s_nop 0
	global_load_lds_dwordx4 v[190:191], off
	s_barrier
; #define PG8_STAGE(bufoff, gbase, voff) do { _Pragma("unroll") for (int _i = 0; _i < 2; ++_i) \
;         __builtin_amdgcn_global_load_lds((const unsigned*)((const char*)(gbase) + (voff)[_i]), (LAS unsigned*)(lds + (bufoff) + ldsw + _i * 8192), 16, 0, 0); } while (0)
; #define PG8_LDA(dst, b, h) do { _Pragma("unroll") for (int m = 0; m < 4; ++m) _Pragma("unroll") for (int k = 0; k < 2; ++k) dst[m][k] = *(const LAS bf16x8*)(lds + PG8_SA(b, h) + aoff + m * 2048 + k * 1024); } while (0)
; #define PG8_MMA(ai, bj, At, Bt) do { __builtin_amdgcn_s_setprio(1); _Pragma("unroll") for (int m = 0; m < 4; ++m) _Pragma("unroll") for (int n = 0; n < 2; ++n) _Pragma("unroll") for (int k = 0; k < 2; ++k) \
;         acc[ai][bj][m][n] = __builtin_amdgcn_mfma_f32_16x16x32_bf16(Bt[n][k], At[m][k], acc[ai][bj][m][n], 0, 0, 0); __builtin_amdgcn_s_setprio(0); } while (0)
; #define PG8_WAIT_V(n) asm volatile("s_waitcnt vmcnt(" #n ")" ::: "memory")
; #define PG8_WAIT_L(n) asm volatile("s_waitcnt lgkmcnt(" #n ")" ::: "memory")
; #define PG8_BAR __builtin_amdgcn_s_barrier()
; #define PG8_SCHED __builtin_amdgcn_sched_barrier(0)
; template <class Epi>
; __device__ __forceinline__ void gemm_phase(LAS unsigned char* lds, const Gemm g, const StaticOrder& S, const Epi& E) {
;     ...
;             PG8_BAR; PG8_WAIT_L(0); PG8_MMA(0, 1, At, B1); PG8_BAR;
;             PG8_LDA(At, 1, 1); PG8_STAGE(PG8_SA(1, 0), a3, voffA);
;             PG8_BAR; PG8_WAIT_L(0); PG8_MMA(1, 0, At, B0); PG8_BAR; PG8_SCHED;
;             PG8_STAGE(PG8_SB(1, 1), b3 + hstep, voffB);
;             PG8_WAIT_V(6); PG8_BAR; PG8_MMA(1, 1, At, B1); PG8_BAR;
;         }
	s_waitcnt lgkmcnt(0)
	s_waitcnt lgkmcnt(0)
	v_mfma_f32_16x16x32_bf16 v[116:119], v[206:209], v[162:165], v[116:119]
	v_mfma_f32_16x16x32_bf16 v[112:115], v[214:217], v[162:165], v[112:115]
	v_mfma_f32_16x16x32_bf16 v[100:103], v[206:209], v[170:173], v[100:103]
	v_mfma_f32_16x16x32_bf16 v[96:99], v[214:217], v[170:173], v[96:99]
	v_mfma_f32_16x16x32_bf16 v[84:87], v[206:209], v[178:181], v[84:87]
	v_mfma_f32_16x16x32_bf16 v[80:83], v[214:217], v[178:181], v[80:83]
	v_mfma_f32_16x16x32_bf16 v[68:71], v[206:209], v[186:189], v[68:71]
	v_mfma_f32_16x16x32_bf16 v[64:67], v[214:217], v[186:189], v[64:67]
	v_mfma_f32_16x16x32_bf16 v[116:119], v[210:213], v[166:169], v[116:119]
	v_mfma_f32_16x16x32_bf16 v[112:115], v[218:221], v[166:169], v[112:115]
	v_mfma_f32_16x16x32_bf16 v[100:103], v[210:213], v[174:177], v[100:103]
	v_mfma_f32_16x16x32_bf16 v[96:99], v[218:221], v[174:177], v[96:99]
	v_mfma_f32_16x16x32_bf16 v[84:87], v[210:213], v[182:185], v[84:87]
	v_mfma_f32_16x16x32_bf16 v[80:83], v[218:221], v[182:185], v[80:83]
	v_mfma_f32_16x16x32_bf16 v[68:71], v[210:213], v[202:205], v[68:71]
	v_mfma_f32_16x16x32_bf16 v[64:67], v[218:221], v[202:205], v[64:67]
	s_mov_b32 m0, s29
	v_lshl_add_u64 v[190:191], v[224:225], 0, s[46:47]
	s_barrier
	ds_read_b128 v[162:165], v148 offset:49152
	ds_read_b128 v[166:169], v148 offset:50176
	ds_read_b128 v[170:173], v148 offset:51200
	ds_read_b128 v[174:177], v148 offset:52224
	ds_read_b128 v[178:181], v148 offset:53248
	ds_read_b128 v[182:185], v148 offset:54272
	ds_read_b128 v[186:189], v148 offset:55296
	ds_read_b128 v[202:205], v148 offset:56320
	global_load_lds_dwordx4 v[190:191], off
	v_lshl_add_u64 v[190:191], v[226:227], 0, s[46:47]
	s_mov_b32 m0, s30
	s_nop 0
	global_load_lds_dwordx4 v[190:191], off
	s_barrier
	s_waitcnt lgkmcnt(0)
	s_waitcnt lgkmcnt(0)
	v_mfma_f32_16x16x32_bf16 v[60:63], v[138:141], v[162:165], v[60:63]
	v_mfma_f32_16x16x32_bf16 v[56:59], v[154:157], v[162:165], v[56:59]
	v_mfma_f32_16x16x32_bf16 v[44:47], v[138:141], v[170:173], v[44:47]
	v_mfma_f32_16x16x32_bf16 v[40:43], v[154:157], v[170:173], v[40:43]
	v_mfma_f32_16x16x32_bf16 v[28:31], v[138:141], v[178:181], v[28:31]
	v_mfma_f32_16x16x32_bf16 v[24:27], v[154:157], v[178:181], v[24:27]
	v_mfma_f32_16x16x32_bf16 v[12:15], v[138:141], v[186:189], v[12:15]
	v_mfma_f32_16x16x32_bf16 v[8:11], v[154:157], v[186:189], v[8:11]
	v_mfma_f32_16x16x32_bf16 v[60:63], v[150:153], v[166:169], v[60:63]
	v_mfma_f32_16x16x32_bf16 v[56:59], v[158:161], v[166:169], v[56:59]
	v_mfma_f32_16x16x32_bf16 v[44:47], v[150:153], v[174:177], v[44:47]
	v_mfma_f32_16x16x32_bf16 v[40:43], v[158:161], v[174:177], v[40:43]
	v_mfma_f32_16x16x32_bf16 v[28:31], v[150:153], v[182:185], v[28:31]
	v_mfma_f32_16x16x32_bf16 v[24:27], v[158:161], v[182:185], v[24:27]
	v_mfma_f32_16x16x32_bf16 v[12:15], v[150:153], v[202:205], v[12:15]
	v_mfma_f32_16x16x32_bf16 v[8:11], v[158:161], v[202:205], v[8:11]
	s_barrier
	s_add_i32 s18, s18, s24
	v_lshl_add_u64 v[138:139], v[228:229], 0, s[46:47]
	s_mov_b32 m0, s18
	s_nop 0
	global_load_lds_dwordx4 v[138:139], off
	v_lshl_add_u64 v[138:139], v[230:231], 0, s[46:47]
	s_add_i32 m0, s18, 0x2000
	s_nop 0
	global_load_lds_dwordx4 v[138:139], off
	s_waitcnt vmcnt(6)
	s_barrier
	v_mfma_f32_16x16x32_bf16 v[52:55], v[206:209], v[162:165], v[52:55]
	v_mfma_f32_16x16x32_bf16 v[48:51], v[214:217], v[162:165], v[48:51]
	v_mfma_f32_16x16x32_bf16 v[36:39], v[206:209], v[170:173], v[36:39]
	v_mfma_f32_16x16x32_bf16 v[32:35], v[214:217], v[170:173], v[32:35]
	v_mfma_f32_16x16x32_bf16 v[20:23], v[206:209], v[178:181], v[20:23]
	v_mfma_f32_16x16x32_bf16 v[16:19], v[214:217], v[178:181], v[16:19]
	v_mfma_f32_16x16x32_bf16 v[4:7], v[206:209], v[186:189], v[4:7]
	v_mfma_f32_16x16x32_bf16 v[0:3], v[214:217], v[186:189], v[0:3]
	v_mfma_f32_16x16x32_bf16 v[52:55], v[210:213], v[166:169], v[52:55]
	v_mfma_f32_16x16x32_bf16 v[48:51], v[218:221], v[166:169], v[48:51]
	v_mfma_f32_16x16x32_bf16 v[36:39], v[210:213], v[174:177], v[36:39]
	v_mfma_f32_16x16x32_bf16 v[32:35], v[218:221], v[174:177], v[32:35]
	v_mfma_f32_16x16x32_bf16 v[20:23], v[210:213], v[182:185], v[20:23]
	v_mfma_f32_16x16x32_bf16 v[16:19], v[218:221], v[182:185], v[16:19]
	v_mfma_f32_16x16x32_bf16 v[4:7], v[210:213], v[202:205], v[4:7]
	v_mfma_f32_16x16x32_bf16 v[0:3], v[218:221], v[202:205], v[0:3]
	s_add_u32 s40, s40, 0x100
	s_addc_u32 s41, s41, 0
	s_add_u32 s16, s16, 0x100
	s_addc_u32 s17, s17, 0
	s_cmp_ge_i32 s42, s31
	s_mov_b32 s18, s42
	s_barrier
	s_cbranch_scc0 .LBB0_528
